# attention: waves 4-7 now take their per-tile barrier late in the P.V part (before the 7th of 8 V groups) instead of between softmax and P.V; their staging DMA follows that barrier
# speedup vs baseline: 1.0312x; 1.0210x over previous
; #define LAS __attribute__((address_space(3)))
; #define ATT_VTR(p) __builtin_bit_cast(s16x4, __builtin_amdgcn_ds_read_tr16_b64_v4i16((LAS s16x4*)(p)))
; DI void attn_unit(LAS unsigned char* lds, const bf16_t* P, bf16_t* Am, int qrow0, int h, int ntiles, int krow_ctx, int krow_lat,
;                   float lam, const float* subw, float outscale) {
;     ...
;     int s0 = 0, s1 = 1, s2 = 2;
;     for (int t = 0; t < ntiles; ++t) {
;         const bool more = (t + 2 < ntiles);
;         if (more) ATT_DMA_KV(t + 2, s2);
;         LAS unsigned char* kp = lds + s0 * 16384 + kb_off;
;         LAS unsigned char* vp0 = lds + s0 * 16384 + vb_par[0];
;         LAS unsigned char* vp1 = lds + s0 * 16384 + vb_par[1];
;         u32x4 pwa[4], pwb[4];
;     ...
;         ATT_QKP(ATT_QA, lsa, pwa);
;         ATT_QKP(ATT_QB, lsb, pwb);
;     ...
;         {
;             s16x4 vl[2][2], vh[2][2];
; #pragma unroll
;             for (int i = 0; i < 2; ++i) { LAS unsigned char* vq = (i ? vp1 : vp0); vl[0][i] = ATT_VTR(vq); vh[0][i] = ATT_VTR(vq + 1024); }
; #pragma unroll
;             for (int gi = 0; gi < 8; ++gi) { const int ks = gi >> 1, dp = gi & 1;
;                 if (gi < 7) { const int ks2 = (gi + 1) >> 1, dp2 = (gi + 1) & 1;
; #pragma unroll
;                     for (int i = 0; i < 2; ++i) { LAS unsigned char* vq = (i ? vp1 : vp0) + dp2 * 8192 + ks2 * 2048; vl[(gi + 1) & 1][i] = ATT_VTR(vq); vh[(gi + 1) & 1][i] = ATT_VTR(vq + 1024); } }
;                 __builtin_amdgcn_sched_barrier(0x406);
; #pragma unroll
;                 for (int i = 0; i < 2; ++i) { const int d0 = 2 * dp + i; const s16x4 lo = vl[gi & 1][i], hh = vh[gi & 1][i];
;                     const bf16x8 vf = {lo[0], lo[1], lo[2], lo[3], hh[0], hh[1], hh[2], hh[3]};
;                     oa[d0] = __builtin_amdgcn_mfma_f32_32x32x16_bf16(vf, __builtin_bit_cast(bf16x8, pwa[ks]), oa[d0], 0, 0, 0);
;                     ob[d0] = __builtin_amdgcn_mfma_f32_32x32x16_bf16(vf, __builtin_bit_cast(bf16x8, pwb[ks]), ob[d0], 0, 0, 0); }
;                 __builtin_amdgcn_sched_barrier(0x406);
;             }
.LBB0_333:
	s_lshl_b32 s0, s5, 14
	s_add_i32 s6, s0, s63
	v_add_u32_e32 v236, s6, v244
	v_add_u32_e32 v232, v236, v222
	ds_read_b128 v[176:179], v232
	v_add_u32_e32 v233, v236, v241
	ds_read_b128 v[180:183], v233
	v_add_u32_e32 v234, v236, v240
	ds_read_b128 v[184:187], v234
	v_add_u32_e32 v235, v236, v248
	ds_read_b128 v[188:191], v235
	ds_read_b128 v[224:227], v253
	ds_read_b128 v[228:231], v253 offset:1024
	ds_read_b128 v[168:171], v253 offset:2048
	ds_read_b128 v[160:163], v253 offset:3072
	v_add_u32_e32 v218, s0, v249
	v_add_u32_e32 v243, s0, v245
	s_add_i32 s4, s4, 1
	s_add_i32 s58, s58, 64
	s_waitcnt lgkmcnt(7)
	v_mfma_f32_32x32x16_bf16 v[128:143], v[176:179], v[144:147], 0
	s_waitcnt lgkmcnt(6)
	v_mfma_f32_32x32x16_bf16 v[128:143], v[180:183], v[148:151], v[128:143]
	s_waitcnt lgkmcnt(5)
	v_mfma_f32_32x32x16_bf16 v[128:143], v[184:187], v[152:155], v[128:143]
	s_waitcnt lgkmcnt(4)
	v_mfma_f32_32x32x16_bf16 v[128:143], v[188:191], v[156:159], v[128:143]
	s_waitcnt lgkmcnt(3)
	v_mfma_f32_32x32x16_bf16 v[192:207], v[176:179], v[224:227], 0
	s_waitcnt lgkmcnt(2)
	v_mfma_f32_32x32x16_bf16 v[192:207], v[180:183], v[228:231], v[192:207]
	s_waitcnt lgkmcnt(1)
	v_mfma_f32_32x32x16_bf16 v[192:207], v[184:187], v[168:171], v[192:207]
	s_waitcnt lgkmcnt(0)
	v_mfma_f32_32x32x16_bf16 v[192:207], v[188:191], v[160:163], v[192:207]
	ds_read_b128 v[176:179], v232 offset:4096
	ds_read_b128 v[180:183], v233 offset:4096
	ds_read_b128 v[184:187], v234 offset:4096
	ds_read_b128 v[188:191], v235 offset:4096
	v_exp_f32_e32 v128, v128
	v_exp_f32_e32 v129, v129
	v_exp_f32_e32 v130, v130
	v_exp_f32_e32 v131, v131
	v_add_f32_e32 v164, v128, v130
	v_add_f32_e32 v165, v129, v131
	v_exp_f32_e32 v132, v132
	v_exp_f32_e32 v133, v133
	v_add_f32_e32 v164, v164, v132
	v_add_f32_e32 v165, v165, v133
	v_exp_f32_e32 v134, v134
	v_exp_f32_e32 v135, v135
	v_add_f32_e32 v164, v164, v134
	v_add_f32_e32 v165, v165, v135
	v_exp_f32_e32 v136, v136
	v_exp_f32_e32 v137, v137
	v_add_f32_e32 v164, v164, v136
	v_add_f32_e32 v165, v165, v137
	v_exp_f32_e32 v138, v138
	v_exp_f32_e32 v139, v139
	v_add_f32_e32 v164, v164, v138
	v_add_f32_e32 v165, v165, v139
	v_exp_f32_e32 v140, v140
	v_exp_f32_e32 v141, v141
	v_add_f32_e32 v164, v164, v140
	v_add_f32_e32 v165, v165, v141
	v_exp_f32_e32 v142, v142
	v_exp_f32_e32 v143, v143
	v_add_f32_e32 v210, v164, v142
	v_add_f32_e32 v212, v165, v143
	v_cvt_pk_bf16_f32 v172, v128, v129
	v_cvt_pk_bf16_f32 v173, v130, v131
	v_cvt_pk_bf16_f32 v174, v132, v133
	v_cvt_pk_bf16_f32 v175, v134, v135
	v_cvt_pk_bf16_f32 v164, v136, v137
	v_cvt_pk_bf16_f32 v165, v138, v139
	v_cvt_pk_bf16_f32 v166, v140, v141
	v_cvt_pk_bf16_f32 v167, v142, v143
	s_waitcnt lgkmcnt(3)
	v_mfma_f32_32x32x16_bf16 v[128:143], v[176:179], v[144:147], 0
	v_exp_f32_e32 v192, v192
	v_exp_f32_e32 v193, v193
	v_exp_f32_e32 v194, v194
	v_exp_f32_e32 v195, v195
	v_add_f32_e32 v236, v192, v194
	v_add_f32_e32 v237, v193, v195
	s_waitcnt lgkmcnt(2)
	v_mfma_f32_32x32x16_bf16 v[128:143], v[180:183], v[148:151], v[128:143]
	v_exp_f32_e32 v196, v196
	v_exp_f32_e32 v197, v197
	v_add_f32_e32 v236, v236, v196
	v_add_f32_e32 v237, v237, v197
	v_exp_f32_e32 v198, v198
	v_exp_f32_e32 v199, v199
	s_waitcnt lgkmcnt(1)
	v_mfma_f32_32x32x16_bf16 v[128:143], v[184:187], v[152:155], v[128:143]
	v_add_f32_e32 v236, v236, v198
	v_add_f32_e32 v237, v237, v199
	v_exp_f32_e32 v200, v200
	v_exp_f32_e32 v201, v201
	v_add_f32_e32 v236, v236, v200
	v_add_f32_e32 v237, v237, v201
	s_waitcnt lgkmcnt(0)
	v_mfma_f32_32x32x16_bf16 v[128:143], v[188:191], v[156:159], v[128:143]
	v_exp_f32_e32 v202, v202
	v_exp_f32_e32 v203, v203
	v_add_f32_e32 v236, v236, v202
	v_add_f32_e32 v237, v237, v203
	v_exp_f32_e32 v204, v204
	v_exp_f32_e32 v205, v205
	v_add_f32_e32 v236, v236, v204
	v_add_f32_e32 v237, v237, v205
	v_exp_f32_e32 v206, v206
	v_exp_f32_e32 v207, v207
	v_add_f32_e32 v211, v236, v206
	v_add_f32_e32 v213, v237, v207
	v_cvt_pk_bf16_f32 v232, v192, v193
	v_cvt_pk_bf16_f32 v233, v194, v195
	v_cvt_pk_bf16_f32 v234, v196, v197
	v_cvt_pk_bf16_f32 v235, v198, v199
	v_cvt_pk_bf16_f32 v236, v200, v201
	v_cvt_pk_bf16_f32 v237, v202, v203
	v_cvt_pk_bf16_f32 v238, v204, v205
	v_cvt_pk_bf16_f32 v239, v206, v207
	v_mfma_f32_32x32x16_bf16 v[192:207], v[176:179], v[224:227], 0
	v_exp_f32_e32 v128, v128
	v_exp_f32_e32 v129, v129
	v_exp_f32_e32 v130, v130
	v_exp_f32_e32 v131, v131
	v_add_f32_e32 v224, v128, v130
	v_add_f32_e32 v225, v129, v131
	v_mfma_f32_32x32x16_bf16 v[192:207], v[180:183], v[228:231], v[192:207]
	v_exp_f32_e32 v132, v132
	v_exp_f32_e32 v133, v133
	v_add_f32_e32 v224, v224, v132
	v_add_f32_e32 v225, v225, v133
	v_exp_f32_e32 v134, v134
	v_exp_f32_e32 v135, v135
	v_mfma_f32_32x32x16_bf16 v[192:207], v[184:187], v[168:171], v[192:207]
	v_add_f32_e32 v224, v224, v134
	v_add_f32_e32 v225, v225, v135
	v_exp_f32_e32 v136, v136
	v_exp_f32_e32 v137, v137
	v_add_f32_e32 v224, v224, v136
	v_add_f32_e32 v225, v225, v137
	v_mfma_f32_32x32x16_bf16 v[192:207], v[188:191], v[160:163], v[192:207]
	v_exp_f32_e32 v138, v138
	v_exp_f32_e32 v139, v139
	v_add_f32_e32 v224, v224, v138
	v_add_f32_e32 v225, v225, v139
	ds_read_b64_tr_b16 v[176:177], v218 offset:49152
	ds_read_b64_tr_b16 v[178:179], v218 offset:50176
	ds_read_b64_tr_b16 v[180:181], v243 offset:49152
	ds_read_b64_tr_b16 v[182:183], v243 offset:50176
	v_exp_f32_e32 v140, v140
	v_exp_f32_e32 v141, v141
	v_add_f32_e32 v224, v224, v140
	v_add_f32_e32 v225, v225, v141
	ds_read_b64_tr_b16 v[184:185], v218 offset:57344
	ds_read_b64_tr_b16 v[186:187], v218 offset:58368
	ds_read_b64_tr_b16 v[188:189], v243 offset:57344
	ds_read_b64_tr_b16 v[190:191], v243 offset:58368
	v_exp_f32_e32 v142, v142
	v_exp_f32_e32 v143, v143
	v_add_f32_e32 v214, v224, v142
	v_add_f32_e32 v216, v225, v143
	v_cvt_pk_bf16_f32 v168, v128, v129
	v_cvt_pk_bf16_f32 v169, v130, v131
	v_cvt_pk_bf16_f32 v170, v132, v133
	v_cvt_pk_bf16_f32 v171, v134, v135
	v_cvt_pk_bf16_f32 v160, v136, v137
	v_cvt_pk_bf16_f32 v161, v138, v139
	v_cvt_pk_bf16_f32 v162, v140, v141
	v_cvt_pk_bf16_f32 v163, v142, v143
	v_exp_f32_e32 v192, v192
	s_waitcnt lgkmcnt(6)
; #define LAS __attribute__((address_space(3)))
; #define ATT_VTR(p) __builtin_bit_cast(s16x4, __builtin_amdgcn_ds_read_tr16_b64_v4i16((LAS s16x4*)(p)))
; DI void attn_unit(LAS unsigned char* lds, const bf16_t* P, bf16_t* Am, int qrow0, int h, int ntiles, int krow_ctx, int krow_lat,
;                   float lam, const float* subw, float outscale) {
;     ...
;         if (more) ATT_DMA_KV(t + 2, s2);
;     ...
;         {
;             s16x4 vl[2][2], vh[2][2];
; #pragma unroll
;             for (int i = 0; i < 2; ++i) { LAS unsigned char* vq = (i ? vp1 : vp0); vl[0][i] = ATT_VTR(vq); vh[0][i] = ATT_VTR(vq + 1024); }
; #pragma unroll
;             for (int gi = 0; gi < 8; ++gi) { const int ks = gi >> 1, dp = gi & 1;
;                 if (gi < 7) { const int ks2 = (gi + 1) >> 1, dp2 = (gi + 1) & 1;
; #pragma unroll
;                     for (int i = 0; i < 2; ++i) { LAS unsigned char* vq = (i ? vp1 : vp0) + dp2 * 8192 + ks2 * 2048; vl[(gi + 1) & 1][i] = ATT_VTR(vq); vh[(gi + 1) & 1][i] = ATT_VTR(vq + 1024); } }
;                 __builtin_amdgcn_sched_barrier(0x406);
; #pragma unroll
;                 for (int i = 0; i < 2; ++i) { const int d0 = 2 * dp + i; const s16x4 lo = vl[gi & 1][i], hh = vh[gi & 1][i];
;                     const bf16x8 vf = {lo[0], lo[1], lo[2], lo[3], hh[0], hh[1], hh[2], hh[3]};
;                     oa[d0] = __builtin_amdgcn_mfma_f32_32x32x16_bf16(vf, __builtin_bit_cast(bf16x8, pwa[ks]), oa[d0], 0, 0, 0);
;                     ob[d0] = __builtin_amdgcn_mfma_f32_32x32x16_bf16(vf, __builtin_bit_cast(bf16x8, pwb[ks]), ob[d0], 0, 0, 0); }
;                 __builtin_amdgcn_sched_barrier(0x406);
;             }
	v_mfma_f32_32x32x16_bf16 v[112:127], v[176:179], v[172:175], v[112:127]
	v_exp_f32_e32 v193, v193
	v_exp_f32_e32 v194, v194
	v_mfma_f32_32x32x16_bf16 v[48:63], v[176:179], v[232:235], v[48:63]
	v_exp_f32_e32 v195, v195
	v_add_f32_e32 v128, v192, v194
	s_waitcnt lgkmcnt(4)
	v_mfma_f32_32x32x16_bf16 v[96:111], v[180:183], v[172:175], v[96:111]
	v_add_f32_e32 v129, v193, v195
	v_exp_f32_e32 v196, v196
	v_mfma_f32_32x32x16_bf16 v[32:47], v[180:183], v[232:235], v[32:47]
	v_exp_f32_e32 v197, v197
	ds_read_b64_tr_b16 v[176:177], v218 offset:51200
	ds_read_b64_tr_b16 v[178:179], v218 offset:52224
	ds_read_b64_tr_b16 v[180:181], v243 offset:51200
	ds_read_b64_tr_b16 v[182:183], v243 offset:52224
	v_add_f32_e32 v128, v128, v196
	v_add_f32_e32 v129, v129, v197
	s_waitcnt lgkmcnt(6)
	v_mfma_f32_32x32x16_bf16 v[80:95], v[184:187], v[172:175], v[80:95]
	v_exp_f32_e32 v198, v198
	v_exp_f32_e32 v199, v199
	v_mfma_f32_32x32x16_bf16 v[16:31], v[184:187], v[232:235], v[16:31]
	v_add_f32_e32 v128, v128, v198
	v_add_f32_e32 v129, v129, v199
	s_waitcnt lgkmcnt(4)
	v_mfma_f32_32x32x16_bf16 v[64:79], v[188:191], v[172:175], v[64:79]
	v_exp_f32_e32 v200, v200
	v_exp_f32_e32 v201, v201
	v_mfma_f32_32x32x16_bf16 v[0:15], v[188:191], v[232:235], v[0:15]
	v_add_f32_e32 v128, v128, v200
	ds_read_b64_tr_b16 v[184:185], v218 offset:59392
	ds_read_b64_tr_b16 v[186:187], v218 offset:60416
	ds_read_b64_tr_b16 v[188:189], v243 offset:59392
	ds_read_b64_tr_b16 v[190:191], v243 offset:60416
	v_add_f32_e32 v129, v129, v201
	v_exp_f32_e32 v202, v202
	s_waitcnt lgkmcnt(6)
	v_mfma_f32_32x32x16_bf16 v[112:127], v[176:179], v[164:167], v[112:127]
	v_exp_f32_e32 v203, v203
	v_add_f32_e32 v128, v128, v202
	v_mfma_f32_32x32x16_bf16 v[48:63], v[176:179], v[236:239], v[48:63]
	v_add_f32_e32 v129, v129, v203
	v_exp_f32_e32 v204, v204
	s_waitcnt lgkmcnt(4)
	v_mfma_f32_32x32x16_bf16 v[96:111], v[180:183], v[164:167], v[96:111]
	v_exp_f32_e32 v205, v205
	v_add_f32_e32 v128, v128, v204
	v_mfma_f32_32x32x16_bf16 v[32:47], v[180:183], v[236:239], v[32:47]
	v_add_f32_e32 v129, v129, v205
	ds_read_b64_tr_b16 v[176:177], v218 offset:53248
	ds_read_b64_tr_b16 v[178:179], v218 offset:54272
	ds_read_b64_tr_b16 v[180:181], v243 offset:53248
	ds_read_b64_tr_b16 v[182:183], v243 offset:54272
	v_exp_f32_e32 v206, v206
	v_exp_f32_e32 v207, v207
	s_waitcnt lgkmcnt(6)
	v_mfma_f32_32x32x16_bf16 v[80:95], v[184:187], v[164:167], v[80:95]
	v_add_f32_e32 v215, v128, v206
	v_add_f32_e32 v217, v129, v207
	v_mfma_f32_32x32x16_bf16 v[16:31], v[184:187], v[236:239], v[16:31]
	v_cvt_pk_bf16_f32 v132, v192, v193
	v_cvt_pk_bf16_f32 v133, v194, v195
	s_waitcnt lgkmcnt(4)
	v_mfma_f32_32x32x16_bf16 v[64:79], v[188:191], v[164:167], v[64:79]
	v_cvt_pk_bf16_f32 v134, v196, v197
	v_cvt_pk_bf16_f32 v135, v198, v199
	v_mfma_f32_32x32x16_bf16 v[0:15], v[188:191], v[236:239], v[0:15]
	v_cvt_pk_bf16_f32 v128, v200, v201
	ds_read_b64_tr_b16 v[184:185], v218 offset:61440
	ds_read_b64_tr_b16 v[186:187], v218 offset:62464
	ds_read_b64_tr_b16 v[188:189], v243 offset:61440
	ds_read_b64_tr_b16 v[190:191], v243 offset:62464
	v_cvt_pk_bf16_f32 v129, v202, v203
	v_cvt_pk_bf16_f32 v130, v204, v205
	v_cvt_pk_bf16_f32 v131, v206, v207
	v_pk_add_f32 v[224:225], v[210:211], v[212:213]
	v_pk_add_f32 v[224:225], v[208:209], v[224:225]
	v_add_f32_e32 v226, v214, v216
	v_add_f32_e32 v227, v215, v217
	v_add_f32_e32 v208, v224, v226
	v_add_f32_e32 v209, v225, v227
	s_waitcnt lgkmcnt(6)
	v_mfma_f32_32x32x16_bf16 v[112:127], v[176:179], v[168:171], v[112:127]
	v_mfma_f32_32x32x16_bf16 v[48:63], v[176:179], v[132:135], v[48:63]
	s_waitcnt lgkmcnt(4)
	v_mfma_f32_32x32x16_bf16 v[96:111], v[180:183], v[168:171], v[96:111]
	v_mfma_f32_32x32x16_bf16 v[32:47], v[180:183], v[132:135], v[32:47]
	ds_read_b64_tr_b16 v[176:177], v218 offset:55296
	ds_read_b64_tr_b16 v[178:179], v218 offset:56320
	ds_read_b64_tr_b16 v[180:181], v243 offset:55296
	ds_read_b64_tr_b16 v[182:183], v243 offset:56320
	s_waitcnt lgkmcnt(6)
	v_mfma_f32_32x32x16_bf16 v[80:95], v[184:187], v[168:171], v[80:95]
	v_mfma_f32_32x32x16_bf16 v[16:31], v[184:187], v[132:135], v[16:31]
	s_waitcnt lgkmcnt(4)
	v_mfma_f32_32x32x16_bf16 v[64:79], v[188:191], v[168:171], v[64:79]
	v_mfma_f32_32x32x16_bf16 v[0:15], v[188:191], v[132:135], v[0:15]
	ds_read_b64_tr_b16 v[184:185], v218 offset:63488
	ds_read_b64_tr_b16 v[186:187], v218 offset:64512
	ds_read_b64_tr_b16 v[188:189], v243 offset:63488
	ds_read_b64_tr_b16 v[190:191], v243 offset:64512
	s_cmp_eq_u32 s38, 0
	s_cbranch_scc1 .Latt_midskip_l
	s_waitcnt vmcnt(0) lgkmcnt(0)
	s_barrier
	s_cmp_gt_u32 s4, s1
	s_cbranch_scc1 .Latt_midskip_l
	s_add_i32 s6, s58, 0xffffffc0
	s_mul_hi_i32 s7, s6, 0x3000
	s_mul_i32 s6, s6, 0x3000
	s_add_u32 s6, s50, s6
	s_addc_u32 s7, s51, s7
	s_add_u32 s8, s6, 0x80
	s_addc_u32 s9, s7, 0
	s_lshl_b32 s10, s60, 14
	s_mov_b32 s11, m0
	s_add_i32 s10, s10, s61
	s_mov_b32 m0, s10
	s_nop 0
	global_load_lds_dwordx4 v251, s[6:7]
	s_addk_i32 s10, 0x2000
	s_mov_b32 m0, s10
	s_nop 0
	global_load_lds_dwordx4 v251, s[8:9]
	s_add_i32 s10, s10, 0xa000
	s_mov_b32 m0, s10
	s_nop 0
	global_load_lds_dwordx4 v252, s[6:7]
	s_addk_i32 s10, 0x2000
	s_mov_b32 m0, s10
	s_nop 0
	global_load_lds_dwordx4 v252, s[8:9]
	s_mov_b32 m0, s11
.Latt_midskip_l:
	s_waitcnt lgkmcnt(6)
	v_mfma_f32_32x32x16_bf16 v[112:127], v[176:179], v[160:163], v[112:127]
	v_mfma_f32_32x32x16_bf16 v[48:63], v[176:179], v[128:131], v[48:63]
	s_waitcnt lgkmcnt(4)
	v_mfma_f32_32x32x16_bf16 v[96:111], v[180:183], v[160:163], v[96:111]
	v_mfma_f32_32x32x16_bf16 v[32:47], v[180:183], v[128:131], v[32:47]
	s_cmp_lg_u32 s38, 0
	s_cbranch_scc1 .Latt_endskip_l
	s_waitcnt vmcnt(0) lgkmcnt(0)
	s_barrier
